# out-proj GEMM second-round tiles deferred into the start of the up-GEMM phase for 40 workgroups (counter-guarded), up GEMM unit order rebalanced
# speedup vs baseline: 1.1008x; 1.0201x over previous
; __global__ void __launch_bounds__(512, 2) hymba_fwd(Params p0) {
;     extern __shared__ __attribute__((aligned(16))) unsigned char smem[];
;     cg::grid_group grid = cg::this_grid();
;     ...
;     for (int phx = p0.ph_lo; phx < p0.ph_hi + (DUP_PHASE >= 0 ? 1 : 0); ++phx) {
;         const int ph = (DUP_PHASE >= 0 && phx > DUP_PHASE) ? phx - 1 : phx;
;         Params p = p0;
;         { size_t z = 0; asm volatile("" : "+s"(z)); p.ws = p0.ws + z; p.out = p0.out + z; }
.LBB0_1:
	s_load_dword s7, s[0:1], 0xf0
	s_load_dwordx4 s[8:11], s[0:1], 0xd8
	s_add_u32 s2, s0, 0xf0
	s_addc_u32 s3, s1, 0
	v_writelane_b32 v254, s2, 3
	v_and_b32_e32 v151, 0x3ff, v0
	v_and_b32_e32 v4, 0x3fffffff, v0
	v_writelane_b32 v254, s3, 4
	s_waitcnt lgkmcnt(0)
	s_abs_i32 s2, s7
	v_cvt_f32_u32_e32 v1, s2
	s_ashr_i32 s3, s7, 31
	v_writelane_b32 v254, s3, 5
	s_lshl_b32 s3, s7, 3
	v_rcp_iflag_f32_e32 v1, v1
	v_writelane_b32 v254, s3, 6
	s_sub_i32 s3, 0, s2
	s_lshl_b32 s47, s7, 9
	v_mul_f32_e32 v0, 0x4f7ffffe, v1
	v_cvt_u32_f32_e32 v0, v0
	v_mov_b32_e32 v149, 0
	v_mov_b32_e32 v152, 1.0
	v_mbcnt_lo_u32_b32 v205, -1, 0
	v_readfirstlane_b32 s4, v0
	s_mul_i32 s3, s3, s4
	s_mul_hi_u32 s3, s4, s3
	s_add_i32 s4, s4, s3
	s_mul_hi_u32 s3, s4, 0x65c
	s_mul_i32 s3, s3, s2
	s_sub_i32 s3, 0x65c, s3
	s_sub_i32 s6, s3, s2
	s_cmp_ge_u32 s3, s2
	s_cselect_b32 s3, s6, s3
	s_sub_i32 s6, s3, s2
	s_cmp_ge_u32 s3, s2
	s_cselect_b32 s3, s6, s3
	s_cmp_lg_u32 s3, 0
	s_cselect_b64 s[12:13], -1, 0
	v_writelane_b32 v254, s12, 7
	s_mul_hi_u32 s5, s4, 0x128
	s_mul_i32 s5, s5, s2
	v_writelane_b32 v254, s13, 8
	v_writelane_b32 v254, s3, 9
	s_sub_i32 s3, s7, s3
	v_writelane_b32 v254, s3, 10
	s_sub_i32 s3, 0x128, s5
	s_sub_i32 s5, s3, s2
	s_cmp_ge_u32 s3, s2
	s_cselect_b32 s3, s5, s3
	s_sub_i32 s5, s3, s2
	s_cmp_ge_u32 s3, s2
	s_cselect_b32 s3, s5, s3
	s_cmp_lg_u32 s3, 0
	s_cselect_b64 s[12:13], -1, 0
	v_writelane_b32 v254, s12, 11
	s_mov_b32 s91, 0x42a00000
	v_mov_b32_e32 v202, 0x358637bd
	v_writelane_b32 v254, s13, 12
	v_writelane_b32 v254, s3, 13
	s_sub_i32 s3, s7, s3
	v_writelane_b32 v254, s3, 14
	s_mul_hi_u32 s3, s4, 0x637
	s_mul_i32 s3, s3, s2
	s_sub_i32 s3, 0x637, s3
	s_sub_i32 s4, s3, s2
	s_cmp_ge_u32 s3, s2
	s_cselect_b32 s3, s4, s3
	s_sub_i32 s4, s3, s2
	s_cmp_ge_u32 s3, s2
	s_cselect_b32 s2, s4, s3
	s_cmp_lg_u32 s2, 0
	s_cselect_b64 s[4:5], -1, 0
	v_writelane_b32 v254, s4, 15
	v_mov_b32_e32 v150, 0x3ecc95a3
	v_mov_b32_e32 v203, 0x154ba000
	v_writelane_b32 v254, s5, 16
	v_writelane_b32 v254, s2, 17
	s_sub_i32 s2, s7, s2
	v_writelane_b32 v254, s2, 18
	s_add_u32 s2, s10, 0xec00000
	v_writelane_b32 v254, s2, 19
	s_addc_u32 s2, s11, 0
	s_bitcmp1_b32 s7, 0
	v_writelane_b32 v254, s2, 20
	s_cselect_b64 s[2:3], -1, 0
	v_writelane_b32 v254, s2, 21
	v_mov_b32_e32 v204, 1
	v_mov_b64_e32 v[154:155], 0x128
	v_writelane_b32 v254, s3, 22
	s_add_u32 s2, s10, 0xa200000
	v_writelane_b32 v254, s2, 23
	s_addc_u32 s2, s11, 0
	v_writelane_b32 v254, s2, 24
	s_add_u32 s2, s8, 0x543a180
	v_writelane_b32 v254, s2, 25
	v_writelane_b32 v254, s8, 26
	s_addc_u32 s2, s9, 0
	v_mov_b64_e32 v[156:157], 0x127
	v_writelane_b32 v254, s9, 27
	v_writelane_b32 v254, s10, 28
	v_writelane_b32 v254, s11, 29
	v_writelane_b32 v254, s2, 30
	v_writelane_b32 v254, s7, 31
	s_lshl_b32 s2, s7, 14
	v_writelane_b32 v254, s2, 32
	s_add_i32 s2, 0, 0x23d00
	v_writelane_b32 v254, s2, 33
	s_add_i32 s2, 0, 0x22c00
	v_writelane_b32 v254, s2, 34
	v_cmp_eq_u32_e64 s[2:3], 0, v4
	s_load_dwordx4 s[4:7], s[0:1], 0xc0
	v_mbcnt_hi_u32_b32 v206, -1, v205
	v_writelane_b32 v254, s2, 35
	v_mov_b32_e32 v207, 0x240e
	v_mov_b64_e32 v[158:159], 0x65b
	v_writelane_b32 v254, s3, 36
	s_load_dwordx2 s[2:3], s[0:1], 0xd0
	v_mov_b64_e32 v[160:161], 0x65c
	v_mov_b32_e32 v208, 0x2005
	v_mov_b32_e32 v209, 0x7fd
	v_mov_b32_e32 v0, v149
	s_waitcnt lgkmcnt(0)
	v_writelane_b32 v254, s2, 37
	v_mov_b32_e32 v1, v149
	v_mov_b32_e32 v2, v149
	v_writelane_b32 v254, s3, 38
	v_writelane_b32 v254, s4, 39
	v_mov_b32_e32 v3, v149
	v_mov_b32_e32 v162, 0x3f317218
	v_writelane_b32 v254, s5, 40
	v_writelane_b32 v254, s6, 41
	v_writelane_b32 v254, s7, 42
	s_load_dwordx16 s[4:19], s[0:1], 0x0
	v_mov_b32_e32 v210, 0x7f800000
	v_mov_b32_e32 v211, 0x7fc00000
	v_mov_b32_e32 v212, 0xff800000
	v_bfrev_b32_e32 v213, 0.5
	s_waitcnt lgkmcnt(0)
	v_writelane_b32 v254, s4, 43
	v_mov_b32_e32 v164, 1.0
	v_mov_b32_e32 v165, v152
	v_writelane_b32 v254, s5, 44
	v_writelane_b32 v254, s6, 45
	v_writelane_b32 v254, s7, 46
	v_writelane_b32 v254, s8, 47
	v_writelane_b32 v254, s9, 48
	v_writelane_b32 v254, s10, 49
	v_writelane_b32 v254, s11, 50
	v_writelane_b32 v254, s12, 51
	v_writelane_b32 v254, s13, 52
	v_writelane_b32 v254, s14, 53
	v_writelane_b32 v254, s15, 54
	v_writelane_b32 v254, s16, 55
	v_writelane_b32 v254, s17, 56
	v_writelane_b32 v254, s18, 57
	v_writelane_b32 v254, s19, 58
	s_load_dwordx16 s[4:19], s[0:1], 0x40
	v_mov_b64_e32 v[166:167], 0x636
	v_mov_b64_e32 v[168:169], 0x637
	s_movk_i32 s45, 0x5600
	s_add_i32 s49, 0, 0x1dc00
	s_waitcnt lgkmcnt(0)
	v_writelane_b32 v254, s4, 59
	s_add_i32 s51, 0, 0x11000
	s_add_i32 s53, 0, 0x19800
	v_writelane_b32 v255, s9, 0
	v_writelane_b32 v255, s10, 1
	v_writelane_b32 v255, s11, 2
	v_writelane_b32 v255, s12, 3
	v_writelane_b32 v255, s13, 4
	v_writelane_b32 v255, s14, 5
	v_writelane_b32 v255, s15, 6
	v_writelane_b32 v254, s5, 60
	v_writelane_b32 v255, s16, 7
	v_writelane_b32 v254, s6, 61
	v_writelane_b32 v255, s17, 8
	v_writelane_b32 v254, s7, 62
	v_writelane_b32 v255, s18, 9
	v_writelane_b32 v254, s8, 63
	v_writelane_b32 v255, s19, 10
	s_load_dwordx16 s[4:19], s[0:1], 0x80
	s_movk_i32 s55, 0x110
	s_mov_b32 s97, 0
	s_mov_b64 s[34:35], 0x80
	s_mov_b32 s90, 0x3db504f3
	s_waitcnt lgkmcnt(0)
	v_writelane_b32 v255, s4, 11
	s_mov_b32 s50, s47
	s_nop 0
	v_writelane_b32 v255, s5, 12
	v_writelane_b32 v255, s6, 13
	v_writelane_b32 v255, s7, 14
	v_writelane_b32 v255, s8, 15
	v_writelane_b32 v255, s9, 16
	v_writelane_b32 v255, s10, 17
	v_writelane_b32 v255, s11, 18
	v_writelane_b32 v255, s12, 19
	v_writelane_b32 v255, s13, 20
	v_writelane_b32 v255, s14, 21
	v_writelane_b32 v255, s15, 22
	v_writelane_b32 v255, s16, 23
	v_writelane_b32 v255, s17, 24
	v_writelane_b32 v255, s18, 25
	v_writelane_b32 v255, s19, 26
	s_mov_b32 s2, 0
	s_nop 0
	v_writelane_b32 v255, s2, 61
	s_movk_i32 s2, 0xb0
	s_nop 0
	v_writelane_b32 v254, s2, 9
	s_movk_i32 s2, 0x50
	s_nop 0
	v_writelane_b32 v254, s2, 10
	s_branch .LBB0_5

; #define LAS __attribute__((address_space(3)))
; __device__ __forceinline__ int opaque_bid() { int t = blockIdx.x; asm volatile("" : "+s"(t)); return t; }
;     __device__ bool next(int i, Unit& u) const {
;         const long L = (long)i * G + c; if (L >= nwg) return false;
;         int wgid = (int)L; { const int q = nwg / NXCD, r = nwg % NXCD, xcd = wgid % NXCD, off = wgid / NXCD; wgid = (xcd < r ? xcd * (q + 1) : r * (q + 1) + (xcd - r) * q) + off; }
;         const int nig = WGM * nN, gid = wgid / nig, fm = gid * WGM, gsz = (nM - fm) < WGM ? (nM - fm) : WGM;
;         u.pm = fm + ((wgid % nig) % gsz); u.pn = (wgid % nig) / gsz; return true;
; __global__ void __launch_bounds__(512, 2) hymba_fwd(Params p0) {
;     ...
;         case 5: if (PH_MASK & 32) { pg8::Gemm g{(const bf16_t*)(p.ws + WS_A2), (const bf16_t*)(p.ws + WS_WUP), MP, N3, 2048}; pg8::StaticOrder S; S.init(MP, N3, gridDim.x, opaque_bid());
;                   Epi3 E{(bf16_t*)(p.ws + WS_UP), (const float*)(p.ws + WS_SS2)}; pg8::gemm_phase((LAS unsigned char*)smem, g, S, E);
.Lp5_gemm_entry:
	v_readlane_b32 s4, v255, 61
	v_readlane_b32 s5, v254, 0
	s_cmp_lg_u32 s4, 0
	s_cbranch_scc1 .Lp5_gemm_go
	s_cmpk_ge_u32 s5, 40
	s_cbranch_scc1 .Lp5_gemm_go
	s_mov_b32 s4, 1
	s_nop 0
	v_writelane_b32 v255, s4, 61
	s_branch .Lp4_entry
.Lp5_gemm_go:
	s_add_u32 s2, s82, 0x3b00000
	s_addc_u32 s3, s83, 0
	v_readlane_b32 s26, v254, 0
	s_waitcnt vmcnt(0)
	v_mov_b32_e32 v18, v151
	s_cmpk_gt_i32 s26, 0x65b
	v_readfirstlane_b32 s27, v18
	s_cbranch_scc1 .LBB0_103
	s_ashr_i32 s28, s26, 31
	s_lshr_b32 s0, s28, 29
	s_add_i32 s6, s26, s0
	s_and_b32 s0, s6, -8
	s_sub_i32 s5, s26, s0
	s_cmp_gt_i32 s5, 3
	s_mov_b64 s[0:1], -1
	s_cbranch_scc0 .LBB0_86
	s_mul_i32 s0, s5, 0xcb
	s_add_i32 s4, s0, 4
	s_mov_b64 s[0:1], 0

; __device__ __forceinline__ int opaque_tid() { int t = threadIdx.x; asm volatile("" : "+v"(t)); return t; }
; #define PG8_STAGE(bufoff, gbase, voff) do { _Pragma("unroll") for (int _i = 0; _i < 2; ++_i) \
;         __builtin_amdgcn_global_load_lds((const unsigned*)((const char*)(gbase) + (voff)[_i]), (LAS unsigned*)(lds + (bufoff) + ldsw + _i * 8192), 16, 0, 0); } while (0)
; #define PG8_WAIT_V(n) asm volatile("s_waitcnt vmcnt(" #n ")" ::: "memory")
; #define PG8_BAR __builtin_amdgcn_s_barrier()
; template <class Epi>
; __device__ __forceinline__ void gemm_phase(LAS unsigned char* lds, const Gemm g, const StaticOrder& S, const Epi& E) {
;     const int tid = opaque_tid(), wid = __builtin_amdgcn_readfirstlane(tid >> 6), lane = tid & 63, wr = wid >> 2, wc = wid & 3, fr = lane & 15, fq = lane >> 4;
;     const int K = g.K, nt = K / BK;
;     unsigned voffA[2], voffB[2];
; #pragma unroll
;     for (int i = 0; i < 2; ++i) { int R, C; stage_rc(tid * 16 + i * 8192, R, C); const int Rb = ((R & ~31) + perm32(R & 31));
;         voffA[i] = (unsigned)(R * K + C) * 2u; voffB[i] = (unsigned)(Rb * K + C) * 2u; }
;     ...
;     const char* cA = (const char*)g.A + (size_t)cur.pm * tstep; const char* cB = (const char*)g.Bt + (size_t)cur.pn * tstep;
;     PG8_STAGE(PG8_SB(0, 0), cB, voffB); PG8_STAGE(PG8_SA(0, 0), cA, voffA); PG8_STAGE(PG8_SB(0, 1), cB + hstep, voffB); PG8_STAGE(PG8_SA(0, 1), cA + hstep, voffA);
;     if (wr == 1) PG8_BAR;
;     PG8_WAIT_V(4); PG8_BAR;
;     PG8_STAGE(PG8_SB(1, 0), cB + kstep, voffB); PG8_STAGE(PG8_SA(1, 0), cA + kstep, voffA); PG8_STAGE(PG8_SB(1, 1), cB + hstep + kstep, voffB);
;     PG8_WAIT_V(6); PG8_BAR;
.LBB0_88:
	s_waitcnt lgkmcnt(0)
	v_ashrrev_i32_e32 v5, 31, v18
	v_lshrrev_b32_e32 v5, 26, v5
	v_add_u32_e32 v5, v18, v5
	v_ashrrev_i32_e32 v12, 6, v5
	v_bfe_i32 v5, v18, 27, 1
	v_lshlrev_b32_e32 v4, 4, v18
	v_lshrrev_b32_e32 v5, 22, v5
	v_add_u32_e32 v5, v4, v5
	v_and_b32_e32 v5, 0xfffffc00, v5
	v_sub_u32_e32 v5, v4, v5
	v_lshrrev_b32_e32 v6, 4, v5
	v_bitop3_b32 v6, v6, v5, 32 bitop3:0x6c
	v_ashrrev_i32_e32 v5, 31, v5
	v_lshrrev_b32_e32 v5, 26, v5
	v_add_u32_e32 v5, v6, v5
	v_ashrrev_i32_e32 v13, 6, v5
	v_lshlrev_b32_e32 v7, 3, v12
	v_mul_i32_i24_e32 v8, 64, v13
	v_and_b32_e32 v7, -16, v7
	v_sub_u32_e32 v6, v6, v8
	v_add_u32_e32 v5, v13, v7
	v_lshlrev_b32_e32 v7, 5, v12
	v_ashrrev_i16_sdwa v6, v204, sext(v6) dst_sel:DWORD dst_unused:UNUSED_PAD src0_sel:DWORD src1_sel:BYTE_0
	v_and_b32_e32 v7, 32, v7
	v_bfe_i32 v14, v6, 0, 16
	v_and_b32_e32 v9, 3, v13
	s_mov_b32 s5, 0xfffe0
	v_add_lshl_u32 v7, v7, v14, 1
	v_add_u32_e32 v4, 0x2000, v4
	v_lshlrev_b32_e32 v6, 1, v5
	v_lshrrev_b32_e32 v8, 2, v5
	v_and_or_b32 v9, v5, s5, v9
	v_lshl_add_u32 v132, v5, 12, v7
	v_ashrrev_i32_e32 v5, 31, v4
	v_lshrrev_b32_e32 v5, 22, v5
	v_add_u32_e32 v5, v4, v5
	v_ashrrev_i32_e32 v15, 10, v5
	v_mul_i32_i24_e32 v5, 0x400, v15
	v_sub_u32_e32 v4, v4, v5
	v_and_b32_e32 v6, 24, v6
	v_and_b32_e32 v8, 4, v8
	v_lshrrev_b32_e32 v5, 4, v4
	v_or3_b32 v6, v9, v8, v6
	v_bitop3_b32 v4, v5, v4, 32 bitop3:0x6c
	v_lshl_add_u32 v148, v6, 12, v7
	v_ashrrev_i32_e32 v6, 31, v4
	v_lshrrev_b32_e32 v6, 26, v6
	s_add_u32 s29, s82, 0x20180000
	v_lshlrev_b32_e32 v5, 3, v15
	v_add_u32_e32 v6, v4, v6
	s_addc_u32 s30, s83, 0
	v_and_b32_e32 v5, -16, v5
	v_ashrrev_i32_e32 v16, 6, v6
	s_add_i32 s0, s4, s0
	v_add_u32_e32 v5, v16, v5
	v_and_b32_e32 v6, 0xc0, v6
	v_and_b32_e32 v8, 3, v16
	s_mul_hi_i32 s4, s0, 0x2e8ba2e9
	v_sub_u32_e32 v4, v4, v6
	v_and_or_b32 v8, v5, s5, v8
	s_lshr_b32 s5, s4, 31
	s_ashr_i32 s4, s4, 6
	v_ashrrev_i16_sdwa v4, v204, sext(v4) dst_sel:DWORD dst_unused:UNUSED_PAD src0_sel:DWORD src1_sel:BYTE_0
	s_add_i32 s4, s4, s5
	v_lshlrev_b32_e32 v7, 5, v15
	v_bfe_i32 v17, v4, 0, 16
	v_lshlrev_b32_e32 v4, 1, v5
	v_lshrrev_b32_e32 v6, 2, v5
	s_lshl_b32 s6, s4, 3
	v_and_b32_e32 v7, 32, v7
	v_and_b32_e32 v4, 24, v4
	v_and_b32_e32 v6, 4, v6
	s_sub_i32 s5, 37, s6
	v_or3_b32 v4, v8, v6, v4
	v_add_lshl_u32 v6, v7, v17, 1
	s_min_u32 s7, s5, 8
	s_mulk_i32 s4, 0x160
	v_lshl_add_u32 v134, v5, 12, v6
	s_sub_i32 s9, s0, s4
	v_cvt_f32_ubyte0_e32 v5, s7
	v_lshl_add_u32 v136, v4, 12, v6
	v_cvt_f32_i32_e32 v4, s9
	v_rcp_iflag_f32_e32 v6, v5
	s_ashr_i32 s8, s27, 6
	s_ashr_i32 s0, s9, 30
	s_ashr_i32 s1, s27, 8
	v_mul_f32_e32 v6, v4, v6
	v_trunc_f32_e32 v6, v6
	v_fma_f32 v4, -v6, v5, v4
	v_cvt_i32_f32_e32 v6, v6
	s_lshl_b32 s31, s8, 10
	s_or_b32 s0, s0, 1
	v_cmp_ge_f32_e64 s[4:5], |v4|, v5
	s_and_b64 s[4:5], s[4:5], exec
	s_cselect_b32 s0, s0, 0
	v_readfirstlane_b32 s4, v6
	s_add_i32 s0, s4, s0
	s_mul_i32 s4, s0, s7
	s_sub_i32 s4, s9, s4
	s_sext_i32_i16 s4, s4
	s_add_i32 s18, s6, s4
	s_sub_i32 s9, s26, 40
	s_cmp_lt_i32 s9, 0
	s_cselect_b32 s10, 0x100, 0
	s_add_i32 s9, s9, s10
	s_and_b32 s0, s9, 7
	s_mul_i32 s0, s0, 0xb0
	s_lshr_b32 s10, s9, 3
	s_add_i32 s0, s0, s10
	s_cmpk_ge_u32 s0, 0x160
	s_cselect_b32 s18, 1, 0
	s_cmpk_ge_u32 s0, 0x2c0
	s_cselect_b32 s10, 1, 0
	s_add_i32 s18, s18, s10
	s_cmpk_ge_u32 s0, 0x420
	s_cselect_b32 s10, 1, 0
	s_add_i32 s18, s18, s10
	s_mul_i32 s10, s18, 0x160
	s_sub_i32 s0, s0, s10
	s_lshl_b32 s18, s18, 3
	s_and_b32 s10, s0, 7
	s_add_i32 s18, s18, s10
	s_lshr_b32 s0, s0, 3
	s_ashr_i32 s19, s18, 31
	s_bfe_i64 s[6:7], s[0:1], 0x100000
	s_lshl_b64 s[4:5], s[18:19], 20
	s_lshl_b64 s[6:7], s[6:7], 20
	s_add_u32 s22, s2, s6
	s_addc_u32 s23, s3, s7
	s_add_i32 s19, s31, 0
	s_add_i32 m0, s19, 0x10000
	v_mov_b32_e32 v137, v149
	global_load_lds_dwordx4 v148, s[22:23]
	s_add_i32 m0, s19, 0x12000
	s_add_u32 s20, s29, s4
	global_load_lds_dwordx4 v136, s[22:23]
	s_addc_u32 s21, s30, s5
	s_mov_b32 m0, s19
	s_add_i32 s33, s19, 0x2000
	global_load_lds_dwordx4 v132, s[20:21]
	s_mov_b32 m0, s33
	s_add_u32 s4, s22, 0x80000
	global_load_lds_dwordx4 v134, s[20:21]
	s_addc_u32 s5, s23, 0
	s_add_i32 m0, s19, 0x14000
	v_mov_b32_e32 v133, v149
	global_load_lds_dwordx4 v148, s[4:5]
	s_add_i32 m0, s19, 0x16000
	v_mov_b32_e32 v135, v149
	global_load_lds_dwordx4 v136, s[4:5]
	s_add_u32 s4, s20, 0x80000
	s_addc_u32 s5, s21, 0
	s_add_i32 s36, s19, 0x4000
	s_mov_b32 m0, s36
	s_add_i32 s37, s19, 0x6000
	global_load_lds_dwordx4 v132, s[4:5]
	s_mov_b32 m0, s37
	v_lshl_add_u64 v[10:11], s[22:23], 0, v[148:149]
	global_load_lds_dwordx4 v134, s[4:5]
	v_lshl_add_u64 v[8:9], s[22:23], 0, v[136:137]
	v_lshl_add_u64 v[6:7], s[20:21], 0, v[132:133]
	s_cmp_lg_u32 s1, 1
	v_lshl_add_u64 v[4:5], s[20:21], 0, v[134:135]
	s_cbranch_scc1 .LBB0_90
	s_barrier

;     __device__ bool next(int i, Unit& u) const {
;         const long L = (long)i * G + c; if (L >= nwg) return false;
;         int wgid = (int)L; { const int q = nwg / NXCD, r = nwg % NXCD, xcd = wgid % NXCD, off = wgid / NXCD; wgid = (xcd < r ? xcd * (q + 1) : r * (q + 1) + (xcd - r) * q) + off; }
;         const int nig = WGM * nN, gid = wgid / nig, fm = gid * WGM, gsz = (nM - fm) < WGM ? (nM - fm) : WGM;
;         u.pm = fm + ((wgid % nig) % gsz); u.pn = (wgid % nig) / gsz; return true;
; template <class Epi>
; __device__ __forceinline__ void gemm_phase(LAS unsigned char* lds, const Gemm g, const StaticOrder& S, const Epi& E) {
;     ...
; #pragma unroll
;         for (int a = 0; a < 2; ++a)
; #pragma unroll
;             for (int b = 0; b < 2; ++b)
; #pragma unroll
;                 for (int m = 0; m < 4; ++m)
; #pragma unroll
;                     for (int n = 0; n < 2; ++n) acc[a][b][m][n] = (f32x4){0.f, 0.f, 0.f, 0.f};
;         cur = nxt; cA = nA; cB = nB; ++ui;
.LBB0_91:
	s_add_i32 s40, s40, 1
	s_sub_i32 s9, s26, 40
	s_cmp_lt_i32 s9, 0
	s_cselect_b32 s13, 0x100, 0
	s_add_i32 s9, s9, s13
	s_mov_b32 s14, -1
	s_cmp_lt_u32 s40, 5
	s_cbranch_scc1 .Lp5_L_regular
	s_cmp_eq_u32 s40, 5
	s_cbranch_scc1 .Lp5_i5
	s_cmp_eq_u32 s40, 6
	s_cbranch_scc0 .Lp5_L_done
	s_cmpk_lt_u32 s9, 0x5c
	s_cbranch_scc1 .Lp5_L_regular
	s_cmpk_lt_u32 s9, 0x60
	s_cbranch_scc1 .Lp5_L_done
	s_cmpk_ge_u32 s9, 0x88
	s_cbranch_scc1 .Lp5_L_done
	s_add_i32 s14, s9, 0x578
	s_branch .Lp5_L_done
.Lp5_i5:
	s_cmpk_ge_u32 s9, 0xd8
	s_cbranch_scc1 .Lp5_L_done
.Lp5_L_regular:
	s_lshl_b32 s14, s40, 8
	s_add_i32 s14, s14, s9
.Lp5_L_done:
	s_cmp_ge_i32 s14, 0
	s_cselect_b64 s[0:1], 0, -1
	s_cbranch_scc0 .LBB0_97
	s_cmpk_ge_u32 s14, 0x580
	s_cbranch_scc1 .Lp5_tail_tile
	s_and_b32 s8, s14, 7
	s_mul_i32 s8, s8, 0xb0
	s_lshr_b32 s13, s14, 3
	s_add_i32 s8, s8, s13
	s_cmpk_ge_u32 s8, 0x160
	s_cselect_b32 s12, 1, 0
	s_cmpk_ge_u32 s8, 0x2c0
	s_cselect_b32 s13, 1, 0
	s_add_i32 s12, s12, s13
	s_cmpk_ge_u32 s8, 0x420
	s_cselect_b32 s13, 1, 0
	s_add_i32 s12, s12, s13
	s_mul_i32 s13, s12, 0x160
	s_sub_i32 s8, s8, s13
	s_lshl_b32 s12, s12, 3
	s_and_b32 s13, s8, 7
	s_add_i32 s12, s12, s13
	s_lshr_b32 s8, s8, 3
	s_branch .LBB0_97
.Lp5_tail_tile:
	s_sub_i32 s9, s14, 0x580
	s_mul_i32 s8, s9, 0xcccd
	s_lshr_b32 s8, s8, 18
	s_mul_i32 s13, s8, 5
	s_sub_i32 s13, s9, s13
	s_add_i32 s12, s13, 32
	s_add_u32 s16, s82, 0x22b32500
	s_addc_u32 s17, s83, 0
	s_mov_b32 s9, 0
.Lp5_wait_deferred:
	global_load_dword v4, v149, s[16:17] sc1
	s_waitcnt vmcnt(0)
	v_readfirstlane_b32 s13, v4
	s_cmpk_ge_u32 s13, 40
	s_cbranch_scc1 .Lp5_deferred_ready
	s_add_i32 s9, s9, 1
	s_cmp_ge_u32 s9, 0x40000
	s_cbranch_scc1 .Lp5_deferred_ready
	s_sleep 4
	s_branch .Lp5_wait_deferred
.Lp5_deferred_ready:
	buffer_inv sc1
	s_waitcnt vmcnt(0)
.LBB0_97:
	s_ashr_i32 s13, s12, 31
	s_cmp_ge_i32 s14, 0
	s_cselect_b64 vcc, -1, 0
	s_lshl_b64 s[14:15], s[12:13], 20
	s_add_u32 s14, s29, s14
	s_addc_u32 s15, s30, s15
	s_and_b64 s[16:17], vcc, exec
	s_cselect_b32 s13, s15, s21
	s_cselect_b32 s42, s14, s20
	s_ashr_i32 s9, s8, 31
	s_lshl_b64 s[16:17], s[8:9], 20
	s_add_u32 s16, s2, s16
	s_addc_u32 s17, s3, s17
	s_and_b64 s[24:25], vcc, exec
	s_cselect_b32 s9, s17, s23
	s_cselect_b32 s43, s16, s22
	s_add_u32 s20, s20, 0x80080
	s_addc_u32 s21, s21, 0
	s_add_u32 s44, s22, 0x100
	v_mov_b32_e32 v4, 0
	s_addc_u32 s46, s23, 0
	s_mov_b32 s47, -2
	v_mov_b32_e32 v5, v4
	v_mov_b32_e32 v6, v4
	v_mov_b32_e32 v7, v4
	v_mov_b32_e32 v8, v4
	v_mov_b32_e32 v9, v4
	v_mov_b32_e32 v10, v4
	v_mov_b32_e32 v11, v4
	v_mov_b32_e32 v20, v4
	v_mov_b32_e32 v21, v4
	v_mov_b32_e32 v22, v4
	v_mov_b32_e32 v23, v4
	v_mov_b32_e32 v24, v4
	v_mov_b32_e32 v25, v4
	v_mov_b32_e32 v26, v4
	v_mov_b32_e32 v27, v4
	v_mov_b32_e32 v36, v4
	v_mov_b32_e32 v37, v4
	v_mov_b32_e32 v38, v4
	v_mov_b32_e32 v39, v4
	v_mov_b32_e32 v40, v4
	v_mov_b32_e32 v41, v4
	v_mov_b32_e32 v42, v4
	v_mov_b32_e32 v43, v4
	v_mov_b32_e32 v52, v4
	v_mov_b32_e32 v53, v4
	v_mov_b32_e32 v54, v4
	v_mov_b32_e32 v55, v4
	v_mov_b32_e32 v56, v4
	v_mov_b32_e32 v57, v4
	v_mov_b32_e32 v58, v4
	v_mov_b32_e32 v59, v4
	v_mov_b32_e32 v12, v4
	v_mov_b32_e32 v13, v4
	v_mov_b32_e32 v14, v4
	v_mov_b32_e32 v15, v4
	v_mov_b32_e32 v16, v4
	v_mov_b32_e32 v17, v4
	v_mov_b32_e32 v18, v4
	v_mov_b32_e32 v19, v4
	v_mov_b32_e32 v28, v4
	v_mov_b32_e32 v29, v4
	v_mov_b32_e32 v30, v4
	v_mov_b32_e32 v31, v4
	v_mov_b32_e32 v32, v4
	v_mov_b32_e32 v33, v4
	v_mov_b32_e32 v34, v4
	v_mov_b32_e32 v35, v4
	v_mov_b32_e32 v44, v4
	v_mov_b32_e32 v45, v4
	v_mov_b32_e32 v46, v4
	v_mov_b32_e32 v47, v4
	v_mov_b32_e32 v48, v4
	v_mov_b32_e32 v49, v4
	v_mov_b32_e32 v50, v4
	v_mov_b32_e32 v51, v4
	v_mov_b32_e32 v60, v4
	v_mov_b32_e32 v61, v4
	v_mov_b32_e32 v62, v4
	v_mov_b32_e32 v63, v4
	v_mov_b32_e32 v64, v4
	v_mov_b32_e32 v65, v4
	v_mov_b32_e32 v66, v4
	v_mov_b32_e32 v67, v4
	v_mov_b32_e32 v68, v4
	v_mov_b32_e32 v69, v4
	v_mov_b32_e32 v70, v4
	v_mov_b32_e32 v71, v4
	v_mov_b32_e32 v72, v4
	v_mov_b32_e32 v73, v4
	v_mov_b32_e32 v74, v4
	v_mov_b32_e32 v75, v4
	v_mov_b32_e32 v84, v4
	v_mov_b32_e32 v85, v4
	v_mov_b32_e32 v86, v4
	v_mov_b32_e32 v87, v4
	v_mov_b32_e32 v88, v4
	v_mov_b32_e32 v89, v4
	v_mov_b32_e32 v90, v4
	v_mov_b32_e32 v91, v4
	v_mov_b32_e32 v100, v4
	v_mov_b32_e32 v101, v4
	v_mov_b32_e32 v102, v4
	v_mov_b32_e32 v103, v4
	v_mov_b32_e32 v104, v4
	v_mov_b32_e32 v105, v4
	v_mov_b32_e32 v106, v4
	v_mov_b32_e32 v107, v4
	v_mov_b32_e32 v116, v4
	v_mov_b32_e32 v117, v4
	v_mov_b32_e32 v118, v4
	v_mov_b32_e32 v119, v4
	v_mov_b32_e32 v120, v4
	v_mov_b32_e32 v121, v4
	v_mov_b32_e32 v122, v4
	v_mov_b32_e32 v123, v4
	v_mov_b32_e32 v76, v4
	v_mov_b32_e32 v77, v4
	v_mov_b32_e32 v78, v4
	v_mov_b32_e32 v79, v4
	v_mov_b32_e32 v80, v4
	v_mov_b32_e32 v81, v4
	v_mov_b32_e32 v82, v4
	v_mov_b32_e32 v83, v4
	v_mov_b32_e32 v92, v4
	v_mov_b32_e32 v93, v4
	v_mov_b32_e32 v94, v4
	v_mov_b32_e32 v95, v4
	v_mov_b32_e32 v96, v4
	v_mov_b32_e32 v97, v4
	v_mov_b32_e32 v98, v4
	v_mov_b32_e32 v99, v4
	v_mov_b32_e32 v108, v4
	v_mov_b32_e32 v109, v4
	v_mov_b32_e32 v110, v4
	v_mov_b32_e32 v111, v4
	v_mov_b32_e32 v112, v4
	v_mov_b32_e32 v113, v4
	v_mov_b32_e32 v114, v4
	v_mov_b32_e32 v115, v4
	v_mov_b32_e32 v124, v4
	v_mov_b32_e32 v125, v4
	v_mov_b32_e32 v126, v4
	v_mov_b32_e32 v127, v4
	v_mov_b32_e32 v128, v4
	v_mov_b32_e32 v129, v4
	v_mov_b32_e32 v130, v4
	v_mov_b32_e32 v131, v4

; #define LAS __attribute__((address_space(3)))
; __device__ __forceinline__ int opaque_bid() { int t = blockIdx.x; asm volatile("" : "+s"(t)); return t; }
;     __device__ bool next(int i, Unit& u) const {
;         const long L = (long)i * G + c; if (L >= nwg) return false;
;         int wgid = (int)L; { const int q = nwg / NXCD, r = nwg % NXCD, xcd = wgid % NXCD, off = wgid / NXCD; wgid = (xcd < r ? xcd * (q + 1) : r * (q + 1) + (xcd - r) * q) + off; }
;         const int nig = WGM * nN, gid = wgid / nig, fm = gid * WGM, gsz = (nM - fm) < WGM ? (nM - fm) : WGM;
;         u.pm = fm + ((wgid % nig) % gsz); u.pn = (wgid % nig) / gsz; return true;
; __global__ void __launch_bounds__(512, 2) hymba_fwd(Params p0) {
;     ...
;         case 4: if (PH_MASK & 16) { pg8::Gemm g{(const bf16_t*)(p.ws + WS_MIX), (const bf16_t*)(p.ws + WS_WOUT), MP, 2048, 4096}; pg8::StaticOrder S; S.init(MP, 2048, gridDim.x, opaque_bid());
;                   Epi2 E{p}; pg8::gemm_phase((LAS unsigned char*)smem, g, S, E);
.Lp4_entry:
	v_readlane_b32 s33, v254, 0
	v_readlane_b32 s0, v255, 61
	s_nop 0
	s_lshl_b32 s0, s0, 8
	s_add_i32 s33, s33, s0
	s_waitcnt vmcnt(0)
	v_mov_b32_e32 v16, v151
	s_cmpk_lt_i32 s33, 0x128
	s_cselect_b64 s[0:1], -1, 0
	s_cmpk_gt_i32 s33, 0x127
	v_readfirstlane_b32 s36, v16
	s_cbranch_scc1 .LBB0_209
	s_ashr_i32 s2, s33, 31
	s_lshr_b32 s2, s2, 29
	s_add_i32 s2, s33, s2
	s_ashr_i32 s3, s2, 3
	s_and_b32 s2, s2, -8
	s_sub_i32 s2, s33, s2
	s_cmp_lt_i32 s2, 0
	s_cselect_b32 s4, 33, 32
	s_mul_i32 s2, s2, s4
	s_add_i32 s2, s2, s3
	s_ashr_i32 s3, s2, 31
	s_lshr_b32 s3, s3, 26
	s_add_i32 s3, s2, s3
	s_ashr_i32 s4, s3, 6
	s_lshl_b32 s4, s4, 3
	s_sub_i32 s5, 37, s4
	s_min_u32 s5, s5, 8
	s_andn2_b32 s3, s3, 63
	s_sub_i32 s6, s2, s3
	s_waitcnt lgkmcnt(0)
	v_cvt_f32_ubyte0_e32 v5, s5
	v_cvt_f32_i32_e32 v4, s6
	v_rcp_iflag_f32_e32 v6, v5
	s_ashr_i32 s2, s6, 30
	s_or_b32 s7, s2, 1
	v_mul_f32_e32 v6, v4, v6
	v_trunc_f32_e32 v6, v6
	v_fma_f32 v4, -v6, v5, v4
	v_cvt_i32_f32_e32 v6, v6
	v_cmp_ge_f32_e64 s[2:3], |v4|, v5
	s_and_b64 s[2:3], s[2:3], exec
	s_cselect_b32 s2, s7, 0
	v_readfirstlane_b32 s3, v6
	s_add_i32 s2, s3, s2
	s_sext_i32_i8 s24, s2
	s_mul_i32 s2, s2, s5
	s_sub_i32 s2, s6, s2
	s_sext_i32_i8 s2, s2
	s_add_i32 s22, s4, s2
.LBB0_209:
	s_cmpk_lt_u32 s33, 0x100
	s_cbranch_scc1 .Lp4_map_done
	s_sub_i32 s2, s33, 0x100
	s_lshr_b32 s22, s2, 3
	s_add_i32 s22, s22, 32
	s_and_b32 s24, s2, 7

;     __device__ bool next(int i, Unit& u) const {
;         const long L = (long)i * G + c; if (L >= nwg) return false;
;         int wgid = (int)L; { const int q = nwg / NXCD, r = nwg % NXCD, xcd = wgid % NXCD, off = wgid / NXCD; wgid = (xcd < r ? xcd * (q + 1) : r * (q + 1) + (xcd - r) * q) + off; }
;         const int nig = WGM * nN, gid = wgid / nig, fm = gid * WGM, gsz = (nM - fm) < WGM ? (nM - fm) : WGM;
;         u.pm = fm + ((wgid % nig) % gsz); u.pn = (wgid % nig) / gsz; return true;
; template <class Epi>
; __device__ __forceinline__ void gemm_phase(LAS unsigned char* lds, const Gemm g, const StaticOrder& S, const Epi& E) {
;     ...
;         const bool has_next = S.next(ui + 1, nxt);
.LBB0_214:
	s_add_i32 s48, s48, 1
	v_readlane_b32 s4, v254, 5
	v_readlane_b32 s15, v254, 31
	s_mul_i32 s4, s48, s4
	s_mul_hi_u32 s5, s48, s15
	s_add_i32 s5, s5, s4
	s_mul_i32 s4, s48, s15
	s_add_u32 s18, s4, s33
	s_addc_u32 s19, s5, s52
	s_add_u32 s18, s18, 0x10000
	s_addc_u32 s19, s19, 0
	v_cmp_gt_i64_e64 s[4:5], s[18:19], v[156:157]
	s_and_b64 vcc, exec, s[4:5]
	s_cbranch_vccnz .LBB0_216
	s_ashr_i32 s14, s18, 31
	s_lshr_b32 s14, s14, 29
	s_add_i32 s14, s18, s14
	s_ashr_i32 s15, s14, 3
	s_and_b32 s14, s14, -8
	s_sub_i32 s14, s18, s14
	s_cmp_lt_i32 s14, 0
	s_cselect_b32 s16, 38, 37
	s_mul_i32 s14, s14, s16
	s_add_i32 s14, s14, s15
	s_ashr_i32 s15, s14, 31
	s_lshr_b32 s15, s15, 26
	s_add_i32 s15, s14, s15
	s_ashr_i32 s16, s15, 6
	s_lshl_b32 s16, s16, 3
	s_sub_i32 s17, 37, s16
	s_min_i32 s17, s17, 8
	s_abs_i32 s20, s17
	v_cvt_f32_u32_e32 v4, s20
	s_sub_i32 s23, 0, s20
	s_andn2_b32 s15, s15, 63
	s_sub_i32 s15, s14, s15
	v_rcp_iflag_f32_e32 v4, v4
	s_abs_i32 s14, s15
	s_xor_b32 s21, s15, s17
	s_ashr_i32 s21, s21, 31
	v_mul_f32_e32 v4, 0x4f7ffffe, v4
	v_cvt_u32_f32_e32 v4, v4
	s_nop 0
	v_readfirstlane_b32 s25, v4
	s_mul_i32 s23, s23, s25
	s_mul_hi_u32 s23, s25, s23
	s_add_i32 s25, s25, s23
	s_mul_hi_u32 s23, s14, s25
	s_mul_i32 s25, s23, s20
	s_sub_i32 s14, s14, s25
	s_add_i32 s30, s23, 1
	s_sub_i32 s25, s14, s20
	s_cmp_ge_u32 s14, s20
	s_cselect_b32 s23, s30, s23
	s_cselect_b32 s14, s25, s14
	s_add_i32 s25, s23, 1
	s_cmp_ge_u32 s14, s20
	s_cselect_b32 s14, s25, s23
	s_xor_b32 s14, s14, s21
	s_sub_i32 s14, s14, s21
	s_mul_i32 s17, s14, s17
	s_sub_i32 s15, s15, s17
	s_add_i32 s16, s16, s15

; #define PG8_WAIT_V(n) asm volatile("s_waitcnt vmcnt(" #n ")" ::: "memory")
; #define PG8_BAR __builtin_amdgcn_s_barrier()
; template <class Epi>
; __device__ __forceinline__ void gemm_phase(LAS unsigned char* lds, const Gemm g, const StaticOrder& S, const Epi& E) {
;     ...
;     PG8_WAIT_V(0);
;     if (wr == 0) PG8_BAR;
;     PG8_BAR;
.LBB0_328:
	s_barrier
	v_readlane_b32 s0, v255, 61
	s_nop 0
	s_cmp_lg_u32 s0, 1
	s_cbranch_scc1 .LBB0_329
	s_mov_b32 s0, 2
	s_nop 0
	v_writelane_b32 v255, s0, 61
	v_cmp_eq_u32_e32 vcc, 0, v151
	s_and_saveexec_b64 s[4:5], vcc
	s_cbranch_execz .Lp4_deferred_published
	buffer_wbl2 sc1
	s_waitcnt vmcnt(0)
	s_add_u32 s0, s82, 0x22b32500
	s_addc_u32 s1, s83, 0
	v_mov_b32_e32 v4, 1
	global_atomic_add v149, v4, s[0:1]
	s_waitcnt vmcnt(0)
.Lp4_deferred_published:
	s_or_b64 exec, exec, s[4:5]
	s_branch .Lp5_gemm_entry
